# sub-XCD barriers only where the consumers overwrite nothing other groups may still read: 4-workgroup groups on G2->G3, G3->G4, G6->G7; 8-workgroup groups on G1->pre, pre->scan, G5->attn; G4->G5, attn-
# baseline (speedup 1.0000x reference)
.LBB0_164:
	s_waitcnt vmcnt(0)
	v_readfirstlane_b32 s0, v194
	s_cmp_gt_u32 s0, 63
	s_waitcnt vmcnt(0)
	s_barrier
	s_cbranch_scc1 .LBB0_218
	v_mbcnt_lo_u32_b32 v0, -1, 0
	v_mbcnt_hi_u32_b32 v0, -1, v0
	s_nop 0
	v_cmp_eq_u32_e32 vcc, 0, v0
	s_and_saveexec_b64 s[0:1], vcc
	s_cbranch_execz .LBB0_217
	v_mov_b32_e32 v0, 0x23ff0
	s_waitcnt vmcnt(0) lgkmcnt(0)
	ds_read_b128 v[0:3], v0
	s_waitcnt lgkmcnt(0)
	v_readfirstlane_b32 s3, v2
	s_nop 0
	s_cmp_eq_u32 s3, 0
	s_cbranch_scc1 .Lfb_slow_0
	v_readfirstlane_b32 s8, v0
	s_cmp_eq_u32 s8, 32
	s_cbranch_scc0 .Lfb_xcd_0
	buffer_inv sc1
	s_getreg_b32 s3, hwreg(HW_REG_XCC_ID, 0, 4)
	s_and_b32 s3, s3, 7
	s_lshl_b32 s3, s3, 8
	s_bfe_u32 s8, s2, 0x20006
	s_lshl_b32 s8, s8, 2
	s_add_u32 s3, s3, s8
	s_add_u32 s3, s3, 0x36e0
	s_add_u32 s4, s92, 0x510000
	s_addc_u32 s5, s93, 0
	v_mov_b32_e32 v6, s3
	v_mov_b32_e32 v7, 1
	v_mov_b32_e32 v5, 8
	global_atomic_add v6, v7, s[4:5]
	s_mov_b32 s8, 0
	s_branch .Lfb_spin_0
.Lfb_xcd_0:
	buffer_inv sc1
	v_add_u32_e32 v3, 1, v3
	v_mov_b32_e32 v4, 0x23ffc
	ds_write_b32 v4, v3
	v_mul_lo_u32 v5, v3, v0
	s_getreg_b32 s3, hwreg(HW_REG_XCC_ID, 0, 4)
	s_and_b32 s3, s3, 7
	s_lshl_b32 s3, s3, 8
	s_add_u32 s3, s3, 0x3680
	s_add_u32 s4, s92, 0x510000
	s_addc_u32 s5, s93, 0
	v_mov_b32_e32 v6, s3
	v_mov_b32_e32 v7, 1
	global_atomic_add v6, v7, s[4:5]
	s_mov_b32 s8, 0

.LBB0_308:
	s_waitcnt vmcnt(0)
	v_readfirstlane_b32 s4, v194
	s_cmp_gt_u32 s4, 63
	v_readlane_b32 s77, v242, 9
	v_readlane_b32 s78, v241, 13
	v_readlane_b32 s40, v241, 12
	v_readlane_b32 s41, v241, 4
	s_barrier
	s_cbranch_scc1 .LBB0_362
	v_mbcnt_lo_u32_b32 v0, -1, 0
	v_mbcnt_hi_u32_b32 v0, -1, v0
	s_nop 0
	v_cmp_eq_u32_e32 vcc, 0, v0
	s_and_saveexec_b64 s[6:7], vcc
	s_cbranch_execz .LBB0_361
	v_mov_b32_e32 v0, 0x23ff0
	s_waitcnt vmcnt(0) lgkmcnt(0)
	ds_read_b128 v[0:3], v0
	s_waitcnt lgkmcnt(0)
	v_readfirstlane_b32 s8, v2
	s_nop 0
	s_cmp_eq_u32 s8, 0
	s_cbranch_scc1 .Lfb_slow_1
	v_readfirstlane_b32 s9, v0
	s_cmp_eq_u32 s9, 32
	s_cbranch_scc0 .Lfb_xcd_1
	buffer_inv sc1
	s_getreg_b32 s8, hwreg(HW_REG_XCC_ID, 0, 4)
	s_and_b32 s8, s8, 7
	s_lshl_b32 s8, s8, 8
	s_bfe_u32 s9, s2, 0x20006
	s_lshl_b32 s9, s9, 2
	s_add_u32 s8, s8, s9
	s_add_u32 s8, s8, 0x36e0
	s_add_u32 s4, s92, 0x510000
	s_addc_u32 s5, s93, 0
	v_mov_b32_e32 v6, s8
	v_mov_b32_e32 v7, 1
	v_mov_b32_e32 v5, 16
	global_atomic_add v6, v7, s[4:5]
	s_mov_b32 s9, 0
	s_branch .Lfb_spin_1
.Lfb_xcd_1:
	buffer_inv sc1
	v_add_u32_e32 v3, 1, v3
	v_mov_b32_e32 v4, 0x23ffc
	ds_write_b32 v4, v3
	v_mul_lo_u32 v5, v3, v0
	s_getreg_b32 s8, hwreg(HW_REG_XCC_ID, 0, 4)
	s_and_b32 s8, s8, 7
	s_lshl_b32 s8, s8, 8
	s_add_u32 s8, s8, 0x3680
	s_add_u32 s4, s92, 0x510000
	s_addc_u32 s5, s93, 0
	v_mov_b32_e32 v6, s8
	v_mov_b32_e32 v7, 1
	global_atomic_add v6, v7, s[4:5]
	s_mov_b32 s9, 0

.LBB0_949:
	s_waitcnt vmcnt(0)
	v_readfirstlane_b32 s0, v194
	s_cmp_gt_u32 s0, 63
	s_waitcnt vmcnt(0)
	s_barrier
	s_cbranch_scc1 .LBB0_1003
	v_mbcnt_lo_u32_b32 v0, -1, 0
	v_mbcnt_hi_u32_b32 v0, -1, v0
	s_nop 0
	v_cmp_eq_u32_e32 vcc, 0, v0
	s_and_saveexec_b64 s[0:1], vcc
	s_cbranch_execz .LBB0_1002
	v_mov_b32_e32 v20, 0x23ff0
	s_waitcnt vmcnt(0) lgkmcnt(0)
	ds_read_b128 v[20:23], v20
	s_waitcnt lgkmcnt(0)
	v_readfirstlane_b32 s3, v22
	s_nop 0
	s_cmp_eq_u32 s3, 0
	s_cbranch_scc1 .Lfb_slow_5
	v_readfirstlane_b32 s8, v20
	s_cmp_eq_u32 s8, 32
	s_cbranch_scc0 .Lfb_xcd_5
	buffer_inv sc1
	s_getreg_b32 s3, hwreg(HW_REG_XCC_ID, 0, 4)
	s_and_b32 s3, s3, 7
	s_lshl_b32 s3, s3, 8
	s_bfe_u32 s8, s2, 0x20006
	s_lshl_b32 s8, s8, 2
	s_add_u32 s3, s3, s8
	s_add_u32 s3, s3, 0x36e0
	s_add_u32 s4, s92, 0x510000
	s_addc_u32 s5, s93, 0
	v_mov_b32_e32 v26, s3
	v_mov_b32_e32 v27, 1
	v_mov_b32_e32 v25, 24
	global_atomic_add v26, v27, s[4:5]
	s_mov_b32 s8, 0
	s_branch .Lfb_spin_5
